# in-proj tile order: multiplicative column-tile permutation (25*pn+1 mod 44) instead of rotation: heavy f32-output tiles spread over rounds within each XCD (max half of an XCD heavy per round)
# speedup vs baseline: 1.0020x; 1.0020x over previous
.LBB0_134:
	s_load_dwordx16 s[4:19], s[0:1], 0x70
	s_cmp_lt_i32 s44, 2
	s_cselect_b64 s[0:1], -1, 0
	s_cmp_gt_i32 s45, 1
	s_cselect_b64 s[2:3], -1, 0
	s_waitcnt lgkmcnt(0)
	v_writelane_b32 v254, s4, 28
	s_and_b64 s[0:1], s[0:1], s[2:3]
	s_andn2_b64 vcc, exec, s[0:1]
	v_writelane_b32 v254, s5, 29
	v_writelane_b32 v254, s6, 30
	v_writelane_b32 v254, s7, 31
	v_writelane_b32 v254, s8, 32
	v_writelane_b32 v254, s9, 33
	v_writelane_b32 v254, s10, 34
	v_writelane_b32 v254, s11, 35
	v_writelane_b32 v254, s12, 36
	v_writelane_b32 v254, s13, 37
	v_writelane_b32 v254, s14, 38
	v_writelane_b32 v254, s15, 39
	v_writelane_b32 v254, s16, 40
	v_writelane_b32 v254, s17, 41
	v_writelane_b32 v254, s18, 42
	v_writelane_b32 v254, s19, 43
	v_writelane_b32 v254, s84, 44
	s_mov_b64 s[0:1], s[44:45]
	s_mov_b32 s2, s46
	v_writelane_b32 v254, s85, 45
	v_writelane_b32 v254, s86, 46
	v_writelane_b32 v254, s87, 47
	v_writelane_b32 v254, s88, 48
	v_writelane_b32 v254, s89, 49
	v_writelane_b32 v254, s90, 50
	v_writelane_b32 v254, s91, 51
	v_writelane_b32 v254, s0, 52
	s_nop 1
	v_writelane_b32 v254, s1, 53
	v_writelane_b32 v254, s2, 54
	v_writelane_b32 v254, s3, 55
	v_writelane_b32 v254, s43, 56
	s_cbranch_vccnz .LBB0_671
	s_cmpk_lt_i32 s43, 0x5ac
	s_cselect_b64 s[2:3], -1, 0
	s_cmpk_gt_i32 s43, 0x5ab
	v_readfirstlane_b32 s8, v0
	s_cbranch_scc1 .LBB0_137
	s_ashr_i32 s0, s43, 31
	s_lshr_b32 s0, s0, 29
	s_add_i32 s0, s43, s0
	s_and_b32 s1, s0, -8
	s_sub_i32 s1, s43, s1
	s_mul_i32 s5, s1, 0xb5
	s_add_i32 s5, s5, 4
	s_ashr_i32 s0, s0, 3
	s_mul_i32 s4, s1, 0xb6
	s_cmp_lt_i32 s1, 4
	s_cselect_b32 s1, s4, s5
	s_add_i32 s1, s1, s0
	s_mul_hi_i32 s0, s1, 0x2e8ba2e9
	s_lshr_b32 s4, s0, 31
	s_ashr_i32 s0, s0, 6
	s_add_i32 s0, s0, s4
	s_lshl_b32 s4, s0, 3
	s_sub_i32 s5, 33, s4
	s_mulk_i32 s0, 0x160
	s_min_u32 s5, s5, 8
	s_sub_i32 s6, s1, s0
	s_sext_i32_i16 s0, s6
	v_cvt_f32_ubyte0_e32 v2, s5
	v_cvt_f32_i32_e32 v1, s0
	v_rcp_iflag_f32_e32 v3, v2
	s_ashr_i32 s0, s0, 30
	s_or_b32 s7, s0, 1
	v_mul_f32_e32 v3, v1, v3
	v_trunc_f32_e32 v3, v3
	v_fma_f32 v1, -v3, v2, v1
	v_cvt_i32_f32_e32 v3, v3
	v_cmp_ge_f32_e64 s[0:1], |v1|, v2
	s_and_b64 s[0:1], s[0:1], exec
	s_cselect_b32 s0, s7, 0
	v_readfirstlane_b32 s1, v3
	s_add_i32 s1, s1, s0
	s_sext_i32_i16 s0, s1
	s_mul_i32 s1, s1, s5
	s_sub_i32 s1, s6, s1
	s_sext_i32_i16 s1, s1
	s_add_i32 s4, s4, s1
	s_mul_i32 s0, s0, 25
	s_add_i32 s0, s0, 1
	s_mul_i32 s1, s0, 0x5d2
	s_lshr_b32 s1, s1, 16
	s_mul_i32 s1, s1, 44
	s_sub_i32 s0, s0, s1

.LBB0_148:
	s_ashr_i32 s1, s1, 3
	s_add_i32 s1, s22, s1
	s_mul_hi_i32 s5, s1, 0x2e8ba2e9
	s_lshr_b32 s20, s5, 31
	s_ashr_i32 s5, s5, 6
	s_add_i32 s5, s5, s20
	s_lshl_b32 s21, s5, 3
	s_sub_i32 s20, 33, s21
	s_min_i32 s22, s20, 8
	s_abs_i32 s20, s22
	v_cvt_f32_u32_e32 v2, s20
	s_sub_i32 s24, 0, s20
	s_mulk_i32 s5, 0x160
	s_sub_i32 s1, s1, s5
	v_rcp_iflag_f32_e32 v2, v2
	s_abs_i32 s5, s1
	s_xor_b32 s23, s1, s22
	s_ashr_i32 s23, s23, 31
	v_mul_f32_e32 v2, 0x4f7ffffe, v2
	v_cvt_u32_f32_e32 v2, v2
	s_nop 0
	v_readfirstlane_b32 s25, v2
	s_mul_i32 s24, s24, s25
	s_mul_hi_u32 s24, s25, s24
	s_add_i32 s25, s25, s24
	s_mul_hi_u32 s24, s5, s25
	s_mul_i32 s25, s24, s20
	s_sub_i32 s5, s5, s25
	s_add_i32 s26, s24, 1
	s_sub_i32 s25, s5, s20
	s_cmp_ge_u32 s5, s20
	s_cselect_b32 s24, s26, s24
	s_cselect_b32 s5, s25, s5
	s_add_i32 s25, s24, 1
	s_cmp_ge_u32 s5, s20
	s_cselect_b32 s5, s25, s24
	s_xor_b32 s5, s5, s23
	s_sub_i32 s20, s5, s23
	s_mul_i32 s5, s20, s22
	s_sub_i32 s1, s1, s5
	s_add_i32 s22, s21, s1
	s_mul_i32 s20, s20, 25
	s_add_i32 s20, s20, 1
	s_mul_i32 s5, s20, 0x5d2
	s_lshr_b32 s5, s5, 16
	s_mul_i32 s5, s5, 44
	s_sub_i32 s20, s20, s5
